# entry code prefetch by every workgroup, seam prefetch still by one in eight
# baseline (speedup 1.0000x reference)
_Z12trunk_kernel2KP:
	s_getpc_b64 s[18:19]
	v_and_b32_e32 v254, 0x3ff, v0
	v_lshlrev_b32_e32 v254, 6, v254
	global_load_dword v255, v254, s[18:19]
